# speedup vs baseline: 1.0490x; 1.0085x over previous
; #define SLOAD(i, key0) do { sr_[i].v = *reinterpret_cast<const bf16x8*>(&Vh[(long)((key0) + vr) * ldv + vc]); \
;     sr_[i].k0 = *reinterpret_cast<const bf16x8*>(&Kh[(long)((key0) + kr0) * ldk + kc0]); \
;     if (k2) sr_[i].k1 = *reinterpret_cast<const bf16x8*>(&Kh[(long)((key0) + kr1) * ldk + kc1]); } while (0)
; #define SWRITE(b, i) do { *(bf16x8*)((char*)V_lds + (b) * SHM_V + vst) = sr_[i].v; \
;     *(bf16x8*)((char*)K_lds + (b) * SHM_K + ksw0) = sr_[i].k0; \
;     if (k2) *(bf16x8*)((char*)K_lds + (b) * SHM_K + ksw1) = sr_[i].k1; } while (0)
; #define SWAIT() asm volatile("s_waitcnt vmcnt(2)" ::: "memory")
; template <int DQK, bool FIX>
; __device__ __forceinline__ void attn_item(const bf16* Qb, const bf16* __restrict__ Kh, const bf16* __restrict__ Vh,
;                                           u16* Ob, int q0, int L, int NT, char* lds, float mC) {
;     ...
;   f32x16 pA0, pA1, pB0, pB1; float mnA = 0.f, mnB = 0.f, alA = 1.f, alB = 1.f; bf16x8 pa0, pa1, pa2, pa3;
;   constexpr int SE = 0, SO = 1;
;   const bool act = (q0 + wid * 32) < L;
;   SLOAD(SE, 0); asm volatile("s_waitcnt vmcnt(0)" ::: "memory"); SWRITE(0, SE); __syncthreads();
;   if (act) { qkt<DQK>(pA0, pA1, K_lds, qr, r32, hi, 0, L); partialSM<DQK, FIX>(pA0, pA1, m_reg, mnA, alA, mC); }
;   SLOAD(SO, KVBLK); if (2 < NT) SLOAD(SE, 2 * KVBLK);
;   SWAIT(); SWRITE(1, SO); __syncthreads();
.LBB0_829:
	v_writelane_b32 v254, s18, 59
	v_writelane_b32 v255, s16, 0
	v_writelane_b32 v255, s19, 1
	s_or_b64 exec, exec, s[2:3]
	v_lshlrev_b64 v[2:3], 8, v[18:19]
	v_mov_b32_e32 v29, v1
	v_lshl_add_u64 v[2:3], s[14:15], 0, v[2:3]
	v_lshl_add_u64 v[2:3], v[2:3], 0, v[28:29]
	s_movk_i32 s2, 0x4000
	v_add_co_u32_e32 v4, vcc, s2, v2
	v_lshlrev_b64 v[18:19], 1, v[26:27]
	s_nop 0
	v_addc_co_u32_e32 v5, vcc, 0, v3, vcc
	global_load_dwordx4 v[68:71], v[4:5], off
	v_lshlrev_b64 v[4:5], 8, v[22:23]
	v_lshl_add_u64 v[4:5], s[12:13], 0, v[4:5]
	v_lshl_add_u64 v[4:5], v[4:5], 0, v[18:19]
	v_add_co_u32_e32 v6, vcc, s2, v4
	s_mov_b32 s2, 0x8000
	s_nop 0
	v_addc_co_u32_e32 v7, vcc, 0, v5, vcc
	v_add_co_u32_e32 v4, vcc, s2, v4
	global_load_dwordx4 v[26:29], v[6:7], off
	s_nop 0
	v_addc_co_u32_e32 v5, vcc, 0, v5, vcc
	v_add_co_u32_e32 v2, vcc, s2, v2
	global_load_dwordx4 v[204:207], v[4:5], off
	s_nop 0
	v_addc_co_u32_e32 v3, vcc, 0, v3, vcc
	global_load_dwordx4 v[114:117], v[2:3], off
	v_add_co_u32_e32 v6, vcc, 0x4000, v4
	s_nop 1
	v_addc_co_u32_e32 v7, vcc, 0, v5, vcc
	global_load_dwordx4 v[118:121], v[6:7], off
	v_and_b32_e32 v159, 63, v158
	v_lshlrev_b32_e32 v72, 4, v159
	v_lshlrev_b32_e32 v67, 3, v159
	v_lshlrev_b32_e32 v73, 1, v159
	s_cmp_lg_u32 0, -1
	v_lshl_add_u64 v[22:23], v[24:25], 0, s[6:7]
	v_and_b32_e32 v24, 7, v158
	v_and_b32_e32 v72, 0xc0, v72
	v_readlane_b32 s12, v254, 35
	v_lshl_add_u64 v[20:21], v[20:21], 0, s[6:7]
	v_mov_b32_e32 v25, v1
	v_and_b32_e32 v73, 32, v73
	v_and_b32_e32 v74, 0x100, v67
	s_cselect_b32 s2, 0, 0
	v_lshl_add_u64 v[18:19], v[22:23], 0, v[18:19]
	v_lshlrev_b32_e32 v24, 4, v24
	v_and_or_b32 v22, v67, 24, v72
	v_readlane_b32 s13, v254, 36
	v_add_u32_e32 v66, 0, v66
	v_add_u32_e32 v31, 0, v31
	v_add_u32_e32 v32, 0, v32
	v_add_u32_e32 v33, 0, v33
	v_mov_b32_e32 v16, v1
	v_mov_b32_e32 v17, v1
	s_add_i32 s3, s2, 0x4000
	v_readlane_b32 s14, v254, 37
	v_readlane_b32 s15, v254, 38
	v_lshl_add_u64 v[146:147], s[12:13], 0, v[18:19]
	v_lshl_add_u64 v[18:19], v[20:21], 0, v[24:25]
	v_or3_b32 v20, v22, v73, v74
	s_waitcnt vmcnt(2)
	v_mov_b32_e32 v2, v1
	v_mov_b32_e32 v3, v1
	v_mov_b32_e32 v4, v1
	v_mov_b32_e32 v5, v1
	v_mov_b32_e32 v6, v1
	v_mov_b32_e32 v7, v1
	v_mov_b32_e32 v8, v1
	v_mov_b32_e32 v9, v1
	v_mov_b32_e32 v10, v1
	v_mov_b32_e32 v11, v1
	v_mov_b32_e32 v12, v1
	v_mov_b32_e32 v13, v1
	v_mov_b32_e32 v14, v1
	v_mov_b32_e32 v15, v1
	v_add_u32_e32 v167, v66, v30
	v_add_u32_e32 v168, v31, v30
	v_add_u32_e32 v169, v32, v30
	v_lshl_add_u64 v[148:149], s[14:15], 0, v[18:19]
	v_add_u32_e32 v166, s2, v20
	v_add_u32_e32 v170, s3, v20
	v_add_u32_e32 v171, v33, v30
	v_mov_b64_e32 v[96:97], v[16:17]
	s_mov_b32 s73, 4
	s_mov_b32 s78, 0
	v_lshlrev_b32_e32 v162, 2, v155
	v_mov_b32_e32 v163, 0
	s_sub_i32 s79, s96, 64
	s_sub_i32 s72, s96, 32
	s_waitcnt vmcnt(3)
	ds_write_b128 v160, v[68:71] offset:16384
	s_waitcnt vmcnt(2)
	ds_write_b128 v161, v[26:29] offset:49152
	v_mov_b64_e32 v[32:33], v[16:17]
	v_mov_b64_e32 v[80:81], v[16:17]
	v_mov_b64_e32 v[30:31], v[14:15]
	v_mov_b64_e32 v[28:29], v[12:13]
	v_mov_b64_e32 v[26:27], v[10:11]
	v_mov_b64_e32 v[24:25], v[8:9]
	v_mov_b64_e32 v[22:23], v[6:7]
	v_mov_b64_e32 v[20:21], v[4:5]
	v_mov_b64_e32 v[18:19], v[2:3]
	v_mov_b64_e32 v[78:79], v[14:15]
	v_mov_b64_e32 v[76:77], v[12:13]
	v_mov_b64_e32 v[74:75], v[10:11]
	v_mov_b64_e32 v[72:73], v[8:9]
	v_mov_b64_e32 v[70:71], v[6:7]
	v_mov_b64_e32 v[68:69], v[4:5]
	v_mov_b64_e32 v[66:67], v[2:3]
	v_mov_b64_e32 v[94:95], v[14:15]
	v_mov_b64_e32 v[92:93], v[12:13]
	v_mov_b64_e32 v[90:91], v[10:11]
	v_mov_b64_e32 v[88:89], v[8:9]
	v_mov_b64_e32 v[86:87], v[6:7]
	v_mov_b64_e32 v[84:85], v[4:5]
	v_mov_b64_e32 v[82:83], v[2:3]
	s_waitcnt lgkmcnt(0)
	s_barrier
	s_waitcnt vmcnt(2)
	ds_write_b128 v161, v[204:207] offset:32768
	v_mov_b32_e32 v202, 0
	s_branch .LBB0_832

; #define SBAR() __builtin_amdgcn_sched_barrier(0)
; #define SLOAD(i, key0) do { sr_[i].v = *reinterpret_cast<const bf16x8*>(&Vh[(long)((key0) + vr) * ldv + vc]); \
;     sr_[i].k0 = *reinterpret_cast<const bf16x8*>(&Kh[(long)((key0) + kr0) * ldk + kc0]); \
;     if (k2) sr_[i].k1 = *reinterpret_cast<const bf16x8*>(&Kh[(long)((key0) + kr1) * ldk + kc1]); } while (0)
; #define SWRITE(b, i) do { *(bf16x8*)((char*)V_lds + (b) * SHM_V + vst) = sr_[i].v; \
;     *(bf16x8*)((char*)K_lds + (b) * SHM_K + ksw0) = sr_[i].k0; \
;     if (k2) *(bf16x8*)((char*)K_lds + (b) * SHM_K + ksw1) = sr_[i].k1; } while (0)
; #define SWAIT() asm volatile("s_waitcnt vmcnt(2)" ::: "memory")
; #define RESC(a) do { if (__any((a) < 1.f)) { if (hi == 0) al_l[r32] = (a); asm volatile("s_waitcnt lgkmcnt(0)" ::: "memory"); \
;     _Pragma("unroll") for (int d = 0; d < 2; ++d) _Pragma("unroll") for (int r = 0; r < 16; ++r) o[d][r] *= al_l[crow(r, hi)]; } } while (0)
; template <int DQK, bool FIX>
; __device__ __forceinline__ void attn_item(const bf16* Qb, const bf16* __restrict__ Kh, const bf16* __restrict__ Vh,
;                                           u16* Ob, int q0, int L, int NT, char* lds, float mC) {
;     ...
;   for (int j = 1; j + 1 < NT; j += 2) {
;     if (act) { SBAR(); qkt<DQK>(pB0, pB1, (bf16*)((char*)K_lds + SHM_K), qr, r32, hi, j * KVBLK, L);
;       finishSM(pA0, pA1, alA, l_reg, pa0, pa1, pa2, pa3); SBAR(); }
;     SLOAD(SO, (j + 2) * KVBLK); SBAR();
;     if (act) { pv_d0(o, vb0, pa0, pa1, pa2, pa3); partialSM<DQK, FIX>(pB0, pB1, m_reg, mnB, alB, mC); }
;     __syncthreads(); SWAIT(); SWRITE(0, SE);
;     if (act) { RESC(alB); } __syncthreads();
;     if (act) { SBAR(); qkt<DQK>(pA0, pA1, K_lds, qr, r32, hi, (j + 1) * KVBLK, L);
;       finishSM(pB0, pB1, alB, l_reg, pa0, pa1, pa2, pa3); SBAR(); }
;     if (j + 3 < NT) SLOAD(SE, (j + 3) * KVBLK); SBAR();
;     if (act) { pv_d0(o, vb0 + (int)SHM_V, pa0, pa1, pa2, pa3); partialSM<DQK, FIX>(pA0, pA1, m_reg, mnA, alA, mC); }
;     __syncthreads(); SWAIT(); SWRITE(1, SO);
;     if (act) { RESC(alA); } __syncthreads();
;   }
.LBB0_831:
	s_or_b64 exec, exec, s[6:7]
	s_waitcnt lgkmcnt(0)
	s_barrier
	s_waitcnt vmcnt(2)
	s_mov_b64 s[6:7], 0x8000
	s_addk_i32 s78, 0x80
	v_lshl_add_u64 v[146:147], v[146:147], 0, s[6:7]
	v_lshl_add_u64 v[148:149], v[148:149], 0, s[6:7]
	s_add_i32 s73, s73, 2
	s_and_b64 vcc, exec, s[2:3]
	s_cbranch_vccz .Lt64b_w
	s_waitcnt vmcnt(0)
.Lt64b_w:
	ds_write_b128 v160, v[122:125] offset:16384
	ds_write_b128 v161, v[126:129] offset:32768
	s_cbranch_vccnz .LBB0_853
.LBB0_832:
	s_and_saveexec_b64 s[2:3], s[8:9]
	s_cbranch_execz .LBB0_838
	s_add_i32 s6, s78, 64
	s_cmp_le_u32 s6, s79
	s_cbranch_scc0 .Lslow64a
	s_and_b64 vcc, exec, s[10:11]
	s_cbranch_vccz .Lslow64a
	ds_read_b128 v[222:225], v167 offset:49152
	ds_read_b128 v[226:229], v168 offset:49152
	ds_read_b128 v[230:233], v167 offset:57344
	ds_read_b128 v[234:237], v168 offset:57344
	ds_read_b128 v[238:241], v169 offset:49152
	ds_read_b128 v[242:245], v169 offset:57344
	ds_read_b128 v[246:249], v171 offset:49152
	ds_read_b128 v[250:253], v171 offset:57344
	v_cvt_pk_bf16_f32 v130, v50, v51
	v_cvt_pk_bf16_f32 v131, v52, v53
	v_cvt_pk_bf16_f32 v132, v54, v55
	v_cvt_pk_bf16_f32 v133, v56, v57
	v_cvt_pk_bf16_f32 v134, v58, v59
	v_cvt_pk_bf16_f32 v135, v60, v61
	v_cvt_pk_bf16_f32 v136, v62, v63
	v_cvt_pk_bf16_f32 v137, v64, v65
	s_waitcnt lgkmcnt(7)
	v_mfma_f32_32x32x16_bf16 v[66:81], v[222:225], v[98:101], 0
	ds_read_b64_tr_b16 v[186:187], v166 offset:0
	ds_read_b64_tr_b16 v[188:189], v166 offset:2048
	ds_read_b64_tr_b16 v[190:191], v166 offset:4096
	ds_read_b64_tr_b16 v[192:193], v166 offset:6144
	v_exp_f32_e32 v34, v34
	v_exp_f32_e32 v35, v35
	v_exp_f32_e32 v36, v36
	s_waitcnt lgkmcnt(10)
	v_mfma_f32_32x32x16_bf16 v[66:81], v[226:229], v[102:105], v[66:81]
	ds_read_b64_tr_b16 v[194:195], v166 offset:8192
	ds_read_b64_tr_b16 v[196:197], v166 offset:10240
	ds_read_b64_tr_b16 v[198:199], v166 offset:12288
	ds_read_b64_tr_b16 v[200:201], v166 offset:14336
	v_exp_f32_e32 v37, v37
	v_exp_f32_e32 v38, v38
	v_exp_f32_e32 v39, v39
	s_waitcnt lgkmcnt(13)
	v_mfma_f32_32x32x16_bf16 v[82:97], v[230:233], v[98:101], 0
	v_exp_f32_e32 v40, v40
	v_exp_f32_e32 v41, v41
	v_exp_f32_e32 v42, v42
	s_waitcnt lgkmcnt(12)
	v_mfma_f32_32x32x16_bf16 v[82:97], v[234:237], v[102:105], v[82:97]
	v_exp_f32_e32 v43, v43
	v_exp_f32_e32 v44, v44
	v_exp_f32_e32 v45, v45
	s_waitcnt lgkmcnt(11)
	v_mfma_f32_32x32x16_bf16 v[66:81], v[238:241], v[106:109], v[66:81]
	v_exp_f32_e32 v46, v46
	v_exp_f32_e32 v47, v47
	v_exp_f32_e32 v48, v48
	s_waitcnt lgkmcnt(10)
	v_mfma_f32_32x32x16_bf16 v[82:97], v[242:245], v[106:109], v[82:97]
	ds_read_b64_tr_b16 v[222:223], v166 offset:512
	ds_read_b64_tr_b16 v[224:225], v166 offset:2560
	ds_read_b64_tr_b16 v[226:227], v166 offset:4608
	ds_read_b64_tr_b16 v[228:229], v166 offset:6656
	v_exp_f32_e32 v49, v49
	v_cvt_pk_bf16_f32 v138, v34, v35
	v_cvt_pk_bf16_f32 v139, v36, v37
	v_cvt_pk_bf16_f32 v140, v38, v39
	s_waitcnt lgkmcnt(13)
	v_mfma_f32_32x32x16_bf16 v[66:81], v[246:249], v[110:113], v[66:81]
	v_cvt_pk_bf16_f32 v141, v40, v41
	v_cvt_pk_bf16_f32 v142, v42, v43
	v_cvt_pk_bf16_f32 v143, v44, v45
	v_cvt_pk_bf16_f32 v144, v46, v47
	s_waitcnt lgkmcnt(12)
	v_mfma_f32_32x32x16_bf16 v[82:97], v[250:253], v[110:113], v[82:97]
	ds_read_b64_tr_b16 v[230:231], v166 offset:8704
	ds_read_b64_tr_b16 v[232:233], v166 offset:10752
	ds_read_b64_tr_b16 v[234:235], v166 offset:12800
	s_waitcnt lgkmcnt(14)
	ds_read_b64_tr_b16 v[236:237], v166 offset:14848
	v_cvt_pk_bf16_f32 v145, v48, v49
	s_or_b64 exec, exec, s[2:3]
	v_lshl_add_u64 v[152:153], v[148:149], 0, s[4:5]
	v_add_co_u32_e32 v122, vcc, 0x2ced0000, v152
	v_lshl_add_u64 v[150:151], v[146:147], 0, s[4:5]
	s_nop 0
	v_addc_co_u32_e32 v123, vcc, 0, v153, vcc
	v_add_co_u32_e32 v126, vcc, 0x119d0000, v150
	global_load_dwordx4 v[122:125], v[122:123], off offset:2048
	s_nop 0
	v_addc_co_u32_e32 v127, vcc, 0, v151, vcc
	global_load_dwordx4 v[126:129], v[126:127], off
	s_and_saveexec_b64 s[2:3], s[8:9]
	s_waitcnt lgkmcnt(14)
	v_mfma_f32_32x32x16_bf16 v[2:17], v[130:133], v[186:189], v[2:17]
	v_add_f32_e32 v252, 0, v50
	v_add_f32_e32 v252, v51, v252
	v_add_f32_e32 v252, v52, v252
	v_add_f32_e32 v252, v53, v252
	v_exp_f32_e32 v66, v66
	v_exp_f32_e32 v67, v67
	s_waitcnt lgkmcnt(12)
	v_mfma_f32_32x32x16_bf16 v[2:17], v[134:137], v[190:193], v[2:17]
	v_add_f32_e32 v252, v54, v252
	v_add_f32_e32 v252, v55, v252
	v_add_f32_e32 v252, v56, v252
	v_add_f32_e32 v252, v57, v252
	v_exp_f32_e32 v68, v68
	v_exp_f32_e32 v69, v69
	s_waitcnt lgkmcnt(10)
	v_mfma_f32_32x32x16_bf16 v[2:17], v[138:141], v[194:197], v[2:17]
	v_add_f32_e32 v252, v58, v252
	v_add_f32_e32 v252, v59, v252
	v_add_f32_e32 v252, v60, v252
	v_add_f32_e32 v252, v61, v252
	v_exp_f32_e32 v70, v70
	v_exp_f32_e32 v71, v71
	s_waitcnt lgkmcnt(8)
	v_mfma_f32_32x32x16_bf16 v[2:17], v[142:145], v[198:201], v[2:17]
	v_add_f32_e32 v252, v62, v252
	v_add_f32_e32 v252, v63, v252
	v_add_f32_e32 v252, v64, v252
	v_add_f32_e32 v252, v65, v252
	v_exp_f32_e32 v72, v72
	v_exp_f32_e32 v73, v73
	s_waitcnt lgkmcnt(6)
	v_mfma_f32_32x32x16_bf16 v[18:33], v[130:133], v[222:225], v[18:33]
	v_add_f32_e32 v252, v34, v252
	v_add_f32_e32 v252, v35, v252
	v_add_f32_e32 v252, v36, v252
	v_add_f32_e32 v252, v37, v252
	v_exp_f32_e32 v74, v74
	v_exp_f32_e32 v75, v75
	s_waitcnt lgkmcnt(4)
	v_mfma_f32_32x32x16_bf16 v[18:33], v[134:137], v[226:229], v[18:33]
	v_add_f32_e32 v252, v38, v252
	v_add_f32_e32 v252, v39, v252
	v_add_f32_e32 v252, v40, v252
	v_add_f32_e32 v252, v41, v252
	v_exp_f32_e32 v76, v76
	v_exp_f32_e32 v77, v77
	s_waitcnt lgkmcnt(2)
	v_mfma_f32_32x32x16_bf16 v[18:33], v[138:141], v[230:233], v[18:33]
	v_add_f32_e32 v252, v42, v252
	v_add_f32_e32 v252, v43, v252
	v_add_f32_e32 v252, v44, v252
	v_add_f32_e32 v252, v45, v252
	v_exp_f32_e32 v78, v78
	v_exp_f32_e32 v79, v79
	s_waitcnt lgkmcnt(0)
	v_mfma_f32_32x32x16_bf16 v[18:33], v[142:145], v[234:237], v[18:33]
	v_add_f32_e32 v252, v46, v252
	v_add_f32_e32 v252, v47, v252
	v_add_f32_e32 v252, v48, v252
	v_add_f32_e32 v252, v49, v252
	v_exp_f32_e32 v80, v80
	v_exp_f32_e32 v81, v81
	v_add_f32_e32 v202, v202, v252
	s_branch .LBB0_842

; #define SBAR() __builtin_amdgcn_sched_barrier(0)
; #define SLOAD(i, key0) do { sr_[i].v = *reinterpret_cast<const bf16x8*>(&Vh[(long)((key0) + vr) * ldv + vc]); \
;     sr_[i].k0 = *reinterpret_cast<const bf16x8*>(&Kh[(long)((key0) + kr0) * ldk + kc0]); \
;     if (k2) sr_[i].k1 = *reinterpret_cast<const bf16x8*>(&Kh[(long)((key0) + kr1) * ldk + kc1]); } while (0)
; template <int D0> __device__ __forceinline__ void pv_one(f32x16& od, int vb, bf16x8 pa0, bf16x8 pa1, bf16x8 pa2, bf16x8 pa3) {
;   const s16x4 l0 = tr_read<v_rd_off(D0, 0, 0)>(vb), h0 = tr_read<v_rd_off(D0, 0, 1)>(vb), l1 = tr_read<v_rd_off(D0, 1, 0)>(vb), h1 = tr_read<v_rd_off(D0, 1, 1)>(vb);
;   const s16x4 l2 = tr_read<v_rd_off(D0, 2, 0)>(vb), h2 = tr_read<v_rd_off(D0, 2, 1)>(vb), l3 = tr_read<v_rd_off(D0, 3, 0)>(vb), h3 = tr_read<v_rd_off(D0, 3, 1)>(vb);
;   asm volatile("s_waitcnt lgkmcnt(0)" ::: "memory"); SBAR();
;     ...
;   od = __builtin_amdgcn_mfma_f32_32x32x16_bf16(pa0, PK(l0, h0), od, 0, 0, 0);
;   od = __builtin_amdgcn_mfma_f32_32x32x16_bf16(pa1, PK(l1, h1), od, 0, 0, 0);
;   od = __builtin_amdgcn_mfma_f32_32x32x16_bf16(pa2, PK(l2, h2), od, 0, 0, 0);
;   od = __builtin_amdgcn_mfma_f32_32x32x16_bf16(pa3, PK(l3, h3), od, 0, 0, 0);
;     ...
; }
; __device__ __forceinline__ void pv_d0(f32x16* o, int vb, bf16x8 pa0, bf16x8 pa1, bf16x8 pa2, bf16x8 pa3) {
;   pv_one<0>(o[0], vb, pa0, pa1, pa2, pa3); pv_one<1>(o[1], vb, pa0, pa1, pa2, pa3);
; }
; template <int DQK, bool FIX>
; __device__ __forceinline__ void attn_item(const bf16* Qb, const bf16* __restrict__ Kh, const bf16* __restrict__ Vh,
;                                           u16* Ob, int q0, int L, int NT, char* lds, float mC) {
;     ...
;     SLOAD(SO, (j + 2) * KVBLK); SBAR();
;     if (act) { pv_d0(o, vb0, pa0, pa1, pa2, pa3); partialSM<DQK, FIX>(pB0, pB1, m_reg, mnB, alB, mC); }
.LBB0_838:
	s_or_b64 exec, exec, s[2:3]
	v_lshl_add_u64 v[152:153], v[148:149], 0, s[4:5]
	v_add_co_u32_e32 v122, vcc, 0x2ced0000, v152
	v_lshl_add_u64 v[150:151], v[146:147], 0, s[4:5]
	s_nop 0
	v_addc_co_u32_e32 v123, vcc, 0, v153, vcc
	v_add_co_u32_e32 v126, vcc, 0x119d0000, v150
	global_load_dwordx4 v[122:125], v[122:123], off offset:2048
	s_nop 0
	v_addc_co_u32_e32 v127, vcc, 0, v151, vcc
	global_load_dwordx4 v[126:129], v[126:127], off
	s_and_saveexec_b64 s[2:3], s[8:9]
	s_cbranch_execz .LBB0_842
	ds_read_b64_tr_b16 v[186:187], v166 offset:0
	ds_read_b64_tr_b16 v[188:189], v166 offset:0x800
	ds_read_b64_tr_b16 v[190:191], v166 offset:0x1000
	ds_read_b64_tr_b16 v[192:193], v166 offset:0x1800
	ds_read_b64_tr_b16 v[194:195], v166 offset:0x2000
	ds_read_b64_tr_b16 v[196:197], v166 offset:0x2800
	ds_read_b64_tr_b16 v[198:199], v166 offset:0x3000
	ds_read_b64_tr_b16 v[200:201], v166 offset:0x3800
	s_waitcnt lgkmcnt(0)
	s_nop 0
	v_mfma_f32_32x32x16_bf16 v[2:17], v[130:133], v[186:189], v[2:17]
	ds_read_b64_tr_b16 v[186:187], v166 offset:0x200
	ds_read_b64_tr_b16 v[188:189], v166 offset:0xa00
	v_mfma_f32_32x32x16_bf16 v[2:17], v[134:137], v[190:193], v[2:17]
	ds_read_b64_tr_b16 v[190:191], v166 offset:0x1200
	ds_read_b64_tr_b16 v[192:193], v166 offset:0x1a00
	v_mfma_f32_32x32x16_bf16 v[2:17], v[138:141], v[194:197], v[2:17]
	ds_read_b64_tr_b16 v[194:195], v166 offset:0x2200
	ds_read_b64_tr_b16 v[196:197], v166 offset:0x2a00
	v_mfma_f32_32x32x16_bf16 v[2:17], v[142:145], v[198:201], v[2:17]
	ds_read_b64_tr_b16 v[198:199], v166 offset:0x3200
	ds_read_b64_tr_b16 v[200:201], v166 offset:0x3a00
	s_waitcnt lgkmcnt(0)
	v_mfma_f32_32x32x16_bf16 v[18:33], v[130:133], v[186:189], v[18:33]
	s_and_b64 vcc, exec, s[10:11]
	v_mfma_f32_32x32x16_bf16 v[18:33], v[134:137], v[190:193], v[18:33]
	v_mfma_f32_32x32x16_bf16 v[18:33], v[138:141], v[194:197], v[18:33]
	v_mfma_f32_32x32x16_bf16 v[18:33], v[142:145], v[198:201], v[18:33]
	s_cbranch_vccnz .LBB0_841
	v_sub_f32_e32 v81, v81, v174
	v_sub_f32_e32 v80, v80, v174
	v_sub_f32_e32 v79, v79, v174
	v_sub_f32_e32 v78, v78, v174
	v_sub_f32_e32 v77, v77, v174
	v_sub_f32_e32 v76, v76, v174
	v_sub_f32_e32 v75, v75, v174
	v_sub_f32_e32 v74, v74, v174
	v_sub_f32_e32 v73, v73, v174
	v_sub_f32_e32 v72, v72, v174
	v_sub_f32_e32 v71, v71, v174
	v_sub_f32_e32 v70, v70, v174
	v_sub_f32_e32 v69, v69, v174
	v_sub_f32_e32 v68, v68, v174
	v_sub_f32_e32 v67, v67, v174
	v_sub_f32_e32 v66, v66, v174
	v_sub_f32_e32 v97, v97, v174
	v_sub_f32_e32 v96, v96, v174
	v_sub_f32_e32 v95, v95, v174
	v_sub_f32_e32 v94, v94, v174
	v_sub_f32_e32 v93, v93, v174
	v_sub_f32_e32 v92, v92, v174
	v_sub_f32_e32 v91, v91, v174
	v_sub_f32_e32 v90, v90, v174
	v_sub_f32_e32 v89, v89, v174
	v_sub_f32_e32 v88, v88, v174
	v_sub_f32_e32 v87, v87, v174
	v_sub_f32_e32 v86, v86, v174
	v_sub_f32_e32 v85, v85, v174
	v_sub_f32_e32 v84, v84, v174
	v_sub_f32_e32 v83, v83, v174
	v_sub_f32_e32 v82, v82, v174

; #define SBAR() __builtin_amdgcn_sched_barrier(0)
; #define SLOAD(i, key0) do { sr_[i].v = *reinterpret_cast<const bf16x8*>(&Vh[(long)((key0) + vr) * ldv + vc]); \
;     sr_[i].k0 = *reinterpret_cast<const bf16x8*>(&Kh[(long)((key0) + kr0) * ldk + kc0]); \
;     if (k2) sr_[i].k1 = *reinterpret_cast<const bf16x8*>(&Kh[(long)((key0) + kr1) * ldk + kc1]); } while (0)
; #define SWRITE(b, i) do { *(bf16x8*)((char*)V_lds + (b) * SHM_V + vst) = sr_[i].v; \
;     *(bf16x8*)((char*)K_lds + (b) * SHM_K + ksw0) = sr_[i].k0; \
;     if (k2) *(bf16x8*)((char*)K_lds + (b) * SHM_K + ksw1) = sr_[i].k1; } while (0)
; #define SWAIT() asm volatile("s_waitcnt vmcnt(2)" ::: "memory")
; #define RESC(a) do { if (__any((a) < 1.f)) { if (hi == 0) al_l[r32] = (a); asm volatile("s_waitcnt lgkmcnt(0)" ::: "memory"); \
;     _Pragma("unroll") for (int d = 0; d < 2; ++d) _Pragma("unroll") for (int r = 0; r < 16; ++r) o[d][r] *= al_l[crow(r, hi)]; } } while (0)
; template <int DQK>
; __device__ __forceinline__ void qkt(f32x16& p0, f32x16& p1, const bf16* Ks, const bf16x8* qr, int r32, int hi, int k0, int L) {
;   p0 = f32x16{}; p1 = f32x16{};
; #pragma unroll
;   for (int d0 = 0; d0 < DQK / 16; ++d0) { int cb = (d0 * 16 + hi * 8) * 2;
;     bf16x8 b0 = *reinterpret_cast<const bf16x8*>((const char*)Ks + KSWZ(r32, cb));
;     bf16x8 b1 = *reinterpret_cast<const bf16x8*>((const char*)Ks + KSWZ(32 + r32, cb));
;     p0 = __builtin_amdgcn_mfma_f32_32x32x16_bf16(b0, qr[d0], p0, 0, 0, 0);
;     p1 = __builtin_amdgcn_mfma_f32_32x32x16_bf16(b1, qr[d0], p1, 0, 0, 0); }
; template <int DQK, bool FIX>
; __device__ __forceinline__ void attn_item(const bf16* Qb, const bf16* __restrict__ Kh, const bf16* __restrict__ Vh,
;                                           u16* Ob, int q0, int L, int NT, char* lds, float mC) {
;     ...
;     __syncthreads(); SWAIT(); SWRITE(0, SE);
;     if (act) { RESC(alB); } __syncthreads();
;     if (act) { SBAR(); qkt<DQK>(pA0, pA1, K_lds, qr, r32, hi, (j + 1) * KVBLK, L);
;       finishSM(pB0, pB1, alB, l_reg, pa0, pa1, pa2, pa3); SBAR(); }
;     if (j + 3 < NT) SLOAD(SE, (j + 3) * KVBLK); SBAR();
.LBB0_842:
	s_or_b64 exec, exec, s[2:3]
	s_waitcnt lgkmcnt(0)
	s_barrier
	s_waitcnt vmcnt(2)
	s_waitcnt vmcnt(2)
	ds_write_b128 v160, v[114:117]
	ds_write_b128 v161, v[118:121] offset:49152
	s_and_saveexec_b64 s[2:3], s[8:9]
	s_cbranch_execz .LBB0_848
	s_add_i32 s6, s78, 0x80
	s_cmp_le_u32 s6, s79
	s_cbranch_scc0 .Lslow64b
	s_and_b64 vcc, exec, s[10:11]
	s_cbranch_vccz .Lslow64b
	ds_read_b128 v[222:225], v167 offset:32768
	ds_read_b128 v[226:229], v168 offset:32768
	ds_read_b128 v[230:233], v167 offset:40960
	ds_read_b128 v[234:237], v168 offset:40960
	ds_read_b128 v[238:241], v169 offset:32768
	ds_read_b128 v[242:245], v169 offset:40960
	ds_read_b128 v[246:249], v171 offset:32768
	ds_read_b128 v[250:253], v171 offset:40960
	v_cvt_pk_bf16_f32 v130, v66, v67
	v_cvt_pk_bf16_f32 v131, v68, v69
	v_cvt_pk_bf16_f32 v132, v70, v71
	v_cvt_pk_bf16_f32 v133, v72, v73
	v_cvt_pk_bf16_f32 v134, v74, v75
	v_cvt_pk_bf16_f32 v135, v76, v77
	v_cvt_pk_bf16_f32 v136, v78, v79
	v_cvt_pk_bf16_f32 v137, v80, v81
	s_waitcnt lgkmcnt(7)
	v_mfma_f32_32x32x16_bf16 v[50:65], v[222:225], v[98:101], 0
	ds_read_b64_tr_b16 v[186:187], v170 offset:0
	ds_read_b64_tr_b16 v[188:189], v170 offset:2048
	ds_read_b64_tr_b16 v[190:191], v170 offset:4096
	ds_read_b64_tr_b16 v[192:193], v170 offset:6144
	v_exp_f32_e32 v82, v82
	v_exp_f32_e32 v83, v83
	v_exp_f32_e32 v84, v84
	s_waitcnt lgkmcnt(10)
	v_mfma_f32_32x32x16_bf16 v[50:65], v[226:229], v[102:105], v[50:65]
	ds_read_b64_tr_b16 v[194:195], v170 offset:8192
	ds_read_b64_tr_b16 v[196:197], v170 offset:10240
	ds_read_b64_tr_b16 v[198:199], v170 offset:12288
	ds_read_b64_tr_b16 v[200:201], v170 offset:14336
	v_exp_f32_e32 v85, v85
	v_exp_f32_e32 v86, v86
	v_exp_f32_e32 v87, v87
	s_waitcnt lgkmcnt(13)
	v_mfma_f32_32x32x16_bf16 v[34:49], v[230:233], v[98:101], 0
	v_exp_f32_e32 v88, v88
	v_exp_f32_e32 v89, v89
	v_exp_f32_e32 v90, v90
	s_waitcnt lgkmcnt(12)
	v_mfma_f32_32x32x16_bf16 v[34:49], v[234:237], v[102:105], v[34:49]
	v_exp_f32_e32 v91, v91
	v_exp_f32_e32 v92, v92
	v_exp_f32_e32 v93, v93
	s_waitcnt lgkmcnt(11)
	v_mfma_f32_32x32x16_bf16 v[50:65], v[238:241], v[106:109], v[50:65]
	v_exp_f32_e32 v94, v94
	v_exp_f32_e32 v95, v95
	v_exp_f32_e32 v96, v96
	s_waitcnt lgkmcnt(10)
	v_mfma_f32_32x32x16_bf16 v[34:49], v[242:245], v[106:109], v[34:49]
	ds_read_b64_tr_b16 v[222:223], v170 offset:512
	ds_read_b64_tr_b16 v[224:225], v170 offset:2560
	ds_read_b64_tr_b16 v[226:227], v170 offset:4608
	ds_read_b64_tr_b16 v[228:229], v170 offset:6656
	v_exp_f32_e32 v97, v97
	v_cvt_pk_bf16_f32 v138, v82, v83
	v_cvt_pk_bf16_f32 v139, v84, v85
	v_cvt_pk_bf16_f32 v140, v86, v87
	s_waitcnt lgkmcnt(13)
	v_mfma_f32_32x32x16_bf16 v[50:65], v[246:249], v[110:113], v[50:65]
	v_cvt_pk_bf16_f32 v141, v88, v89
	v_cvt_pk_bf16_f32 v142, v90, v91
	v_cvt_pk_bf16_f32 v143, v92, v93
	v_cvt_pk_bf16_f32 v144, v94, v95
	s_waitcnt lgkmcnt(12)
	v_mfma_f32_32x32x16_bf16 v[34:49], v[250:253], v[110:113], v[34:49]
	ds_read_b64_tr_b16 v[230:231], v170 offset:8704
	ds_read_b64_tr_b16 v[232:233], v170 offset:10752
	ds_read_b64_tr_b16 v[234:235], v170 offset:12800
	s_waitcnt lgkmcnt(14)
	ds_read_b64_tr_b16 v[236:237], v170 offset:14848
	v_cvt_pk_bf16_f32 v145, v96, v97
	s_or_b64 exec, exec, s[2:3]
	s_cmp_ge_u32 s73, s97
	s_cselect_b64 s[2:3], -1, 0
	s_and_b64 vcc, exec, s[2:3]
	s_cbranch_vccnz .Lfast64b_nl
	v_add_co_u32_e32 v114, vcc, 0x2ced4000, v152
	s_nop 1
	v_addc_co_u32_e32 v115, vcc, 0, v153, vcc
	v_add_co_u32_e32 v118, vcc, 0x119d4000, v150
	global_load_dwordx4 v[114:117], v[114:115], off offset:2048
	s_nop 0
	v_addc_co_u32_e32 v119, vcc, 0, v151, vcc
	global_load_dwordx4 v[118:121], v[118:119], off

; #define SBAR() __builtin_amdgcn_sched_barrier(0)
; #define SLOAD(i, key0) do { sr_[i].v = *reinterpret_cast<const bf16x8*>(&Vh[(long)((key0) + vr) * ldv + vc]); \
;     sr_[i].k0 = *reinterpret_cast<const bf16x8*>(&Kh[(long)((key0) + kr0) * ldk + kc0]); \
;     if (k2) sr_[i].k1 = *reinterpret_cast<const bf16x8*>(&Kh[(long)((key0) + kr1) * ldk + kc1]); } while (0)
; template <int DQK, bool FIX>
; __device__ __forceinline__ void attn_item(const bf16* Qb, const bf16* __restrict__ Kh, const bf16* __restrict__ Vh,
;                                           u16* Ob, int q0, int L, int NT, char* lds, float mC) {
;     ...
;     if (act) { SBAR(); qkt<DQK>(pA0, pA1, K_lds, qr, r32, hi, (j + 1) * KVBLK, L);
;       finishSM(pB0, pB1, alB, l_reg, pa0, pa1, pa2, pa3); SBAR(); }
;     if (j + 3 < NT) SLOAD(SE, (j + 3) * KVBLK); SBAR();
.LBB0_848:
	s_or_b64 exec, exec, s[2:3]
	s_cmp_ge_u32 s73, s97
	s_cselect_b64 s[2:3], -1, 0
	s_and_b64 vcc, exec, s[2:3]
	s_cbranch_vccnz .LBB0_850
	v_add_co_u32_e32 v114, vcc, 0x2ced4000, v152
	s_nop 1
	v_addc_co_u32_e32 v115, vcc, 0, v153, vcc
	v_add_co_u32_e32 v118, vcc, 0x119d4000, v150
	global_load_dwordx4 v[114:117], v[114:115], off offset:2048
	s_nop 0
	v_addc_co_u32_e32 v119, vcc, 0, v151, vcc
	global_load_dwordx4 v[118:121], v[118:119], off

; __device__ __forceinline__ int v_st(int k, int c) { const int kk = (k & ~0xC) | ((k & 4) << 1) | ((k & 8) >> 1); return ((kk >> 3) * 4 + (c >> 5)) * 512 + ((kk & 7) * 32 + (c & 31)) * 2; }
; __device__ __forceinline__ int v_rd_base(int lane) { return ((lane & 3) << 3) | (((lane >> 2) & 3) << 6) | (((lane >> 4) & 1) << 5) | (((lane >> 5) & 1) << 8); }
; #define SLOAD(i, key0) do { sr_[i].v = *reinterpret_cast<const bf16x8*>(&Vh[(long)((key0) + vr) * ldv + vc]); \
;     sr_[i].k0 = *reinterpret_cast<const bf16x8*>(&Kh[(long)((key0) + kr0) * ldk + kc0]); \
;     if (k2) sr_[i].k1 = *reinterpret_cast<const bf16x8*>(&Kh[(long)((key0) + kr1) * ldk + kc1]); } while (0)
; #define SWRITE(b, i) do { *(bf16x8*)((char*)V_lds + (b) * SHM_V + vst) = sr_[i].v; \
;     *(bf16x8*)((char*)K_lds + (b) * SHM_K + ksw0) = sr_[i].k0; \
;     if (k2) *(bf16x8*)((char*)K_lds + (b) * SHM_K + ksw1) = sr_[i].k1; } while (0)
; template <int DQK, bool FIX>
; __device__ __forceinline__ void attn_item(const bf16* Qb, const bf16* __restrict__ Kh, const bf16* __restrict__ Vh,
;                                           u16* Ob, int q0, int L, int NT, char* lds, float mC) {
;     ...
;   float m_reg = -1e30f, l_reg = 0; f32x16 o[2] = {}; bf16x8 qr[ND];
;   __syncthreads();
;   { int qrow = q0 + wid * 32 + r32; if (qrow > L - 1) qrow = L - 1;
;     const bf16* Qw = Qb + (long)qrow * ldq + hi * 8;
; #pragma unroll
;     for (int d0 = 0; d0 < ND; ++d0) qr[d0] = *reinterpret_cast<const bf16x8*>(Qw + d0 * 16); }
;   const int vr = tid >> 3, vc = (tid & 7) * 8, vst = v_st(vr, vc);
;   const int kr0 = tid / KCH, kc0 = (tid % KCH) * 8, kr1 = (tid + 512) / KCH, kc1 = ((tid + 512) % KCH) * 8;
;   const bool k2 = (DQK == 96) && (tid < 256);
;   const int ksw0 = KSWZ(kr0, kc0 * 2), ksw1 = KSWZ(kr1, kc1 * 2);
;   const int vb0 = (int)(uintptr_t)V_lds + v_rd_base(lane);
;   struct { bf16x8 v, k0, k1; } sr_[2];
;     ...
;   f32x16 pA0, pA1, pB0, pB1; float mnA = 0.f, mnB = 0.f, alA = 1.f, alB = 1.f; bf16x8 pa0, pa1, pa2, pa3;
;   constexpr int SE = 0, SO = 1;
;   const bool act = (q0 + wid * 32) < L;
;   SLOAD(SE, 0); asm volatile("s_waitcnt vmcnt(0)" ::: "memory"); SWRITE(0, SE); __syncthreads();
;   if (act) { qkt<DQK>(pA0, pA1, K_lds, qr, r32, hi, 0, L); partialSM<DQK, FIX>(pA0, pA1, m_reg, mnA, alA, mC); }
;   SLOAD(SO, KVBLK); if (2 < NT) SLOAD(SE, 2 * KVBLK);
;   SWAIT(); SWRITE(1, SO); __syncthreads();
.LBB0_877:
	s_or_b64 exec, exec, s[6:7]
	v_add_co_u32_e32 v12, vcc, 0x20000, v12
	v_add_u32_e32 v14, 0x80, v30
	s_nop 0
	v_addc_co_u32_e32 v13, vcc, 0, v13, vcc
	global_load_dwordx4 v[144:147], v[12:13], off
	v_mov_b64_e32 v[12:13], s[2:3]
	v_mad_i64_i32 v[12:13], s[4:5], v14, s65, v[12:13]
	v_lshl_add_u64 v[12:13], v[18:19], 1, v[12:13]
	global_load_dwordx4 v[222:225], v[12:13], off
	v_add_co_u32_e32 v12, vcc, 0x18000, v12
	s_nop 1
	v_addc_co_u32_e32 v13, vcc, 0, v13, vcc
	global_load_dwordx4 v[148:151], v[12:13], off
	s_and_saveexec_b64 s[6:7], s[8:9]
	s_cbranch_execz .LBB0_879
	v_add_u32_e32 v14, 0x80, v28
	v_mov_b64_e32 v[12:13], s[2:3]
	v_mad_i64_i32 v[12:13], s[2:3], v14, s65, v[12:13]
	v_lshl_add_u64 v[12:13], v[22:23], 1, v[12:13]
	global_load_dwordx4 v[226:229], v[12:13], off
	v_add_co_u32_e32 v12, vcc, 0x18000, v12
	s_nop 1
	v_addc_co_u32_e32 v13, vcc, 0, v13, vcc
	global_load_dwordx4 v[136:139], v[12:13], off
.LBB0_879:
	s_or_b64 exec, exec, s[6:7]
	s_waitcnt vmcnt(2)
	s_waitcnt vmcnt(3)
	ds_write_b128 v193, v[2:5] offset:16384
	s_waitcnt vmcnt(2)
	ds_write_b128 v194, v[6:9] offset:49152
	s_and_saveexec_b64 s[2:3], s[8:9]
	ds_write_b128 v195, v[140:143] offset:49152
	s_or_b64 exec, exec, s[2:3]
	v_lshlrev_b32_e32 v3, 4, v192
	v_lshlrev_b32_e32 v2, 3, v192
	v_and_b32_e32 v3, 0xc0, v3
	v_lshlrev_b32_e32 v4, 1, v192
	v_and_or_b32 v3, v2, 24, v3
	v_and_b32_e32 v4, 32, v4
	v_and_b32_e32 v2, 0x100, v2
	s_cmp_lg_u32 0, -1
	v_or3_b32 v2, v3, v4, v2
	s_cselect_b32 s2, 0, 0
	v_add_u32_e32 v197, s2, v2
	s_addk_i32 s2, 0x4000
	s_lshr_b32 s16, s19, 1
	v_and_b32_e32 v3, 0x70, v31
	v_or_b32_e32 v4, 32, v0
	v_add_u32_e32 v199, s2, v2
	s_mul_i32 s2, s16, 0xc0
	s_mul_i32 s3, s18, 0x60
	v_xad_u32 v17, v4, v3, 0
	v_or_b32_e32 v4, 64, v0
	s_add_i32 s2, s2, s3
	v_xad_u32 v24, v4, v3, 0
	v_or_b32_e32 v4, 0x60, v0
	s_ashr_i32 s3, s2, 31
	v_xad_u32 v16, v0, v3, 0
	v_xad_u32 v25, v4, v3, 0
	v_or_b32_e32 v4, 0x80, v0
	v_or_b32_e32 v0, 0xa0, v0
	s_lshl_b64 s[6:7], s[2:3], 1
	s_mul_hi_u32 s2, s82, 0x600
	s_mul_i32 s3, s82, 0x600
	v_xad_u32 v26, v4, v3, 0
	v_xad_u32 v27, v0, v3, 0
	v_mov_b32_e32 v2, s3
	v_mov_b32_e32 v3, s2
	v_mad_i64_i32 v[2:3], s[2:3], v28, s65, v[2:3]
	v_readlane_b32 s20, v254, 35
	v_lshl_add_u64 v[2:3], v[22:23], 1, v[2:3]
	v_readlane_b32 s21, v254, 36
	s_sub_i32 s5, s96, 64
	s_sub_i32 s78, s96, 32
	v_lshl_add_u64 v[166:167], s[20:21], 0, v[2:3]
	v_mad_u64_u32 v[2:3], s[2:3], s82, v185, v[10:11]
	s_lshl_b32 s2, s16, 7
	s_lshl_b32 s3, s18, 6
	s_add_i32 s2, s2, s3
	v_lshl_add_u64 v[2:3], v[18:19], 1, v[2:3]
	s_ashr_i32 s3, s2, 31
	v_lshl_add_u64 v[168:169], s[20:21], 0, v[2:3]
	v_lshl_add_u64 v[2:3], v[20:21], 0, s[14:15]
	v_and_b32_e32 v0, 7, v176
	s_lshl_b64 s[2:3], s[2:3], 1
	v_readlane_b32 s14, v254, 57
	v_lshlrev_b32_e32 v0, 4, v0
	s_add_u32 s2, s14, s2
	v_readlane_b32 s14, v254, 58
	v_lshl_add_u64 v[2:3], v[2:3], 0, v[0:1]
	s_addc_u32 s3, s14, s3
	v_mov_b32_e32 v14, v1
	v_mov_b32_e32 v15, v1
	v_lshl_add_u64 v[170:171], s[2:3], 0, v[2:3]
	v_mov_b32_e32 v0, v1
	v_mov_b32_e32 v2, v1
	v_mov_b32_e32 v3, v1
	v_mov_b32_e32 v4, v1
	v_mov_b32_e32 v5, v1
	v_mov_b32_e32 v6, v1
	v_mov_b32_e32 v7, v1
	v_mov_b32_e32 v8, v1
	v_mov_b32_e32 v9, v1
	v_mov_b32_e32 v10, v1
	v_mov_b32_e32 v11, v1
	v_mov_b32_e32 v12, v1
	v_mov_b32_e32 v13, v1
	v_add_u32_e32 v200, v16, v29
	v_add_u32_e32 v201, v17, v29
	v_add_u32_e32 v202, v24, v29
	v_add_u32_e32 v203, v25, v29
	v_add_u32_e32 v204, v26, v29
	v_add_u32_e32 v205, v27, v29
	v_mov_b64_e32 v[46:47], v[14:15]
	v_mov_b64_e32 v[30:31], v[14:15]
	v_mov_b64_e32 v[94:95], v[14:15]
	v_mov_b64_e32 v[110:111], v[14:15]
	s_mov_b32 s79, 4
	s_mov_b32 s4, 0
	v_lshlrev_b32_e32 v196, 2, v189
	v_mov_b32_e32 v198, 0
	v_mov_b64_e32 v[44:45], v[12:13]
	v_mov_b64_e32 v[42:43], v[10:11]
	v_mov_b64_e32 v[40:41], v[8:9]
	v_mov_b64_e32 v[38:39], v[6:7]
	v_mov_b64_e32 v[36:37], v[4:5]
	v_mov_b64_e32 v[34:35], v[2:3]
	v_mov_b64_e32 v[32:33], v[0:1]
	v_mov_b64_e32 v[28:29], v[12:13]
	v_mov_b64_e32 v[26:27], v[10:11]
	v_mov_b64_e32 v[24:25], v[8:9]
	v_mov_b64_e32 v[22:23], v[6:7]
	v_mov_b64_e32 v[20:21], v[4:5]
	v_mov_b64_e32 v[18:19], v[2:3]
	v_mov_b64_e32 v[16:17], v[0:1]
	v_mov_b64_e32 v[92:93], v[12:13]
	v_mov_b64_e32 v[90:91], v[10:11]
	v_mov_b64_e32 v[88:89], v[8:9]
	v_mov_b64_e32 v[86:87], v[6:7]
	v_mov_b64_e32 v[84:85], v[4:5]
	v_mov_b64_e32 v[82:83], v[2:3]
	v_mov_b64_e32 v[80:81], v[0:1]
	v_mov_b64_e32 v[108:109], v[12:13]
	v_mov_b64_e32 v[106:107], v[10:11]
	v_mov_b64_e32 v[104:105], v[8:9]
	v_mov_b64_e32 v[102:103], v[6:7]
	v_mov_b64_e32 v[100:101], v[4:5]
	v_mov_b64_e32 v[98:99], v[2:3]
	v_mov_b64_e32 v[96:97], v[0:1]
	s_waitcnt lgkmcnt(0)
	s_barrier
	s_waitcnt vmcnt(1)
	ds_write_b128 v194, v[222:225] offset:32768
	s_and_saveexec_b64 s[2:3], s[8:9]
	ds_write_b128 v195, v[226:229] offset:32768
	s_or_b64 exec, exec, s[2:3]
	v_readlane_b32 s22, v254, 37
	v_readlane_b32 s23, v254, 38
	v_mov_b32_e32 v186, 0
	s_branch .LBB0_883
; #define SBAR() __builtin_amdgcn_sched_barrier(0)
; #define SLOAD(i, key0) do { sr_[i].v = *reinterpret_cast<const bf16x8*>(&Vh[(long)((key0) + vr) * ldv + vc]); \
;     sr_[i].k0 = *reinterpret_cast<const bf16x8*>(&Kh[(long)((key0) + kr0) * ldk + kc0]); \
;     if (k2) sr_[i].k1 = *reinterpret_cast<const bf16x8*>(&Kh[(long)((key0) + kr1) * ldk + kc1]); } while (0)
; template <int DQK>
; __device__ __forceinline__ void qkt(f32x16& p0, f32x16& p1, const bf16* Ks, const bf16x8* qr, int r32, int hi, int k0, int L) {
;   p0 = f32x16{}; p1 = f32x16{};
; #pragma unroll
;   for (int d0 = 0; d0 < DQK / 16; ++d0) { int cb = (d0 * 16 + hi * 8) * 2;
;     bf16x8 b0 = *reinterpret_cast<const bf16x8*>((const char*)Ks + KSWZ(r32, cb));
;     bf16x8 b1 = *reinterpret_cast<const bf16x8*>((const char*)Ks + KSWZ(32 + r32, cb));
;     p0 = __builtin_amdgcn_mfma_f32_32x32x16_bf16(b0, qr[d0], p0, 0, 0, 0);
;     p1 = __builtin_amdgcn_mfma_f32_32x32x16_bf16(b1, qr[d0], p1, 0, 0, 0); }
; template <int DQK, bool FIX>
; __device__ __forceinline__ void attn_item(const bf16* Qb, const bf16* __restrict__ Kh, const bf16* __restrict__ Vh,
;                                           u16* Ob, int q0, int L, int NT, char* lds, float mC) {
;     ...
;   for (int j = 1; j + 1 < NT; j += 2) {
;     if (act) { SBAR(); qkt<DQK>(pB0, pB1, (bf16*)((char*)K_lds + SHM_K), qr, r32, hi, j * KVBLK, L);
;       finishSM(pA0, pA1, alA, l_reg, pa0, pa1, pa2, pa3); SBAR(); }
;     SLOAD(SO, (j + 2) * KVBLK); SBAR();
;     if (act) { pv_d0(o, vb0, pa0, pa1, pa2, pa3); partialSM<DQK, FIX>(pB0, pB1, m_reg, mnB, alB, mC); }
.LBB0_882:
	s_or_b64 exec, exec, s[14:15]
	s_mov_b64 s[14:15], 0x30000
	v_lshl_add_u64 v[166:167], v[166:167], 0, s[14:15]
	v_lshl_add_u64 v[168:169], v[168:169], 0, s[14:15]
	s_mov_b64 s[14:15], 0x20000
	s_addk_i32 s4, 0x80
	v_lshl_add_u64 v[170:171], v[170:171], 0, s[14:15]
	s_add_i32 s79, s79, 2
	s_and_b64 vcc, exec, s[2:3]
	s_cbranch_vccnz .LBB0_913
.LBB0_883:
	s_and_saveexec_b64 s[2:3], s[10:11]
	s_cbranch_execz .LBB0_889
	s_add_i32 s14, s4, 64
	s_cmp_le_u32 s14, s5
	s_cbranch_scc0 .Lslow96a
	s_and_b64 vcc, exec, s[12:13]
	s_cbranch_vccz .Lslow96a
	ds_read_b128 v[222:225], v200 offset:49152
	ds_read_b128 v[226:229], v200 offset:57344
	ds_read_b128 v[230:233], v201 offset:49152
	ds_read_b128 v[234:237], v201 offset:57344
	ds_read_b128 v[238:241], v202 offset:49152
	ds_read_b128 v[242:245], v202 offset:57344
	ds_read_b128 v[246:249], v203 offset:49152
	ds_read_b128 v[250:253], v203 offset:57344
	v_cvt_pk_bf16_f32 v10, v64, v65
	v_cvt_pk_bf16_f32 v11, v66, v67
	v_cvt_pk_bf16_f32 v12, v68, v69
	v_cvt_pk_bf16_f32 v13, v70, v71
	v_cvt_pk_bf16_f32 v152, v72, v73
	v_cvt_pk_bf16_f32 v153, v74, v75
	v_cvt_pk_bf16_f32 v154, v76, v77
	v_cvt_pk_bf16_f32 v155, v78, v79
	s_waitcnt lgkmcnt(7)
	v_mfma_f32_32x32x16_bf16 v[80:95], v[222:225], v[112:115], 0
	ds_read_b128 v[222:225], v204 offset:49152
	ds_read_b64_tr_b16 v[206:207], v197 offset:0
	ds_read_b64_tr_b16 v[208:209], v197 offset:2048
	ds_read_b64_tr_b16 v[210:211], v197 offset:4096
	ds_read_b64_tr_b16 v[212:213], v197 offset:6144
	v_exp_f32_e32 v48, v48
	v_exp_f32_e32 v49, v49
	v_add_f32_e32 v0, 0, v64
	s_waitcnt lgkmcnt(11)
	v_mfma_f32_32x32x16_bf16 v[96:111], v[226:229], v[112:115], 0
	ds_read_b128 v[226:229], v204 offset:57344
	ds_read_b64_tr_b16 v[214:215], v197 offset:8192
	ds_read_b64_tr_b16 v[216:217], v197 offset:10240
	ds_read_b64_tr_b16 v[218:219], v197 offset:12288
	s_waitcnt lgkmcnt(14)
	ds_read_b64_tr_b16 v[220:221], v197 offset:14336
	v_exp_f32_e32 v50, v50
	v_exp_f32_e32 v51, v51
	v_add_f32_e32 v0, v65, v0
	v_mfma_f32_32x32x16_bf16 v[80:95], v[230:233], v[116:119], v[80:95]
	s_waitcnt lgkmcnt(14)
	ds_read_b128 v[230:233], v205 offset:49152
	v_exp_f32_e32 v52, v52
	v_exp_f32_e32 v53, v53
	v_add_f32_e32 v0, v66, v0
	v_mfma_f32_32x32x16_bf16 v[96:111], v[234:237], v[116:119], v[96:111]
	s_waitcnt lgkmcnt(14)
	ds_read_b128 v[234:237], v205 offset:57344
	v_exp_f32_e32 v54, v54
	v_exp_f32_e32 v55, v55
	v_add_f32_e32 v0, v67, v0
	v_mfma_f32_32x32x16_bf16 v[80:95], v[238:241], v[120:123], v[80:95]
	v_exp_f32_e32 v56, v56
	v_exp_f32_e32 v57, v57
	v_add_f32_e32 v0, v68, v0
	s_waitcnt lgkmcnt(14)
	v_mfma_f32_32x32x16_bf16 v[96:111], v[242:245], v[120:123], v[96:111]
	v_exp_f32_e32 v58, v58
	v_exp_f32_e32 v59, v59
	v_add_f32_e32 v0, v69, v0
	s_waitcnt lgkmcnt(13)
	v_mfma_f32_32x32x16_bf16 v[80:95], v[246:249], v[124:127], v[80:95]
	v_exp_f32_e32 v60, v60
	v_exp_f32_e32 v61, v61
	v_add_f32_e32 v0, v70, v0
	s_waitcnt lgkmcnt(12)
	v_mfma_f32_32x32x16_bf16 v[96:111], v[250:253], v[124:127], v[96:111]
	v_exp_f32_e32 v62, v62
	v_exp_f32_e32 v63, v63
	v_add_f32_e32 v0, v71, v0
	s_waitcnt lgkmcnt(11)
	v_mfma_f32_32x32x16_bf16 v[80:95], v[222:225], v[128:131], v[80:95]
	ds_read_b64_tr_b16 v[238:239], v197 offset:512
	ds_read_b64_tr_b16 v[240:241], v197 offset:2560
	ds_read_b64_tr_b16 v[242:243], v197 offset:4608
	ds_read_b64_tr_b16 v[244:245], v197 offset:6656
	v_cvt_pk_bf16_f32 v156, v48, v49
	v_cvt_pk_bf16_f32 v157, v50, v51
	v_cvt_pk_bf16_f32 v158, v52, v53
	v_cvt_pk_bf16_f32 v159, v54, v55
	v_add_f32_e32 v0, v72, v0
	v_add_f32_e32 v0, v73, v0
	s_waitcnt lgkmcnt(10)
	v_mfma_f32_32x32x16_bf16 v[96:111], v[226:229], v[128:131], v[96:111]
	v_cvt_pk_bf16_f32 v160, v56, v57
	v_cvt_pk_bf16_f32 v161, v58, v59
	v_cvt_pk_bf16_f32 v162, v60, v61
	v_cvt_pk_bf16_f32 v163, v62, v63
	v_add_f32_e32 v0, v74, v0
	v_add_f32_e32 v0, v75, v0
	s_waitcnt lgkmcnt(5)
	v_mfma_f32_32x32x16_bf16 v[80:95], v[230:233], v[132:135], v[80:95]
	ds_read_b64_tr_b16 v[246:247], v197 offset:8704
	ds_read_b64_tr_b16 v[248:249], v197 offset:10752
	ds_read_b64_tr_b16 v[250:251], v197 offset:12800
	ds_read_b64_tr_b16 v[252:253], v197 offset:14848
	v_add_f32_e32 v0, v76, v0
	v_add_f32_e32 v0, v77, v0
	s_waitcnt lgkmcnt(8)
	v_mfma_f32_32x32x16_bf16 v[96:111], v[234:237], v[132:135], v[96:111]
	v_add_f32_e32 v0, v78, v0
	v_add_f32_e32 v0, v79, v0
	s_or_b64 exec, exec, s[2:3]
	v_add_co_u32_e32 v2, vcc, 0xffff0000, v170
	v_lshl_add_u64 v[14:15], v[168:169], 0, s[6:7]
	s_nop 0
	v_addc_co_u32_e32 v3, vcc, -1, v171, vcc
	v_add_co_u32_e32 v6, vcc, 0xa160000, v14
	global_load_dwordx4 v[2:5], v[2:3], off
	s_nop 0
	v_addc_co_u32_e32 v7, vcc, 0, v15, vcc
	global_load_dwordx4 v[6:9], v[6:7], off
	s_and_saveexec_b64 s[2:3], s[8:9]
	s_cbranch_execz .Lfast96a_k2
	v_lshl_add_u64 v[140:141], v[166:167], 0, s[6:7]
	v_add_co_u32_e32 v140, vcc, 0xa160000, v140
	s_nop 1
	v_addc_co_u32_e32 v141, vcc, 0, v141, vcc
	global_load_dwordx4 v[140:143], v[140:141], off

; #define SBAR() __builtin_amdgcn_sched_barrier(0)
; #define SLOAD(i, key0) do { sr_[i].v = *reinterpret_cast<const bf16x8*>(&Vh[(long)((key0) + vr) * ldv + vc]); \
;     sr_[i].k0 = *reinterpret_cast<const bf16x8*>(&Kh[(long)((key0) + kr0) * ldk + kc0]); \
;     if (k2) sr_[i].k1 = *reinterpret_cast<const bf16x8*>(&Kh[(long)((key0) + kr1) * ldk + kc1]); } while (0)
; template <int DQK, bool FIX>
; __device__ __forceinline__ void attn_item(const bf16* Qb, const bf16* __restrict__ Kh, const bf16* __restrict__ Vh,
;                                           u16* Ob, int q0, int L, int NT, char* lds, float mC) {
;     ...
;   for (int j = 1; j + 1 < NT; j += 2) {
;     if (act) { SBAR(); qkt<DQK>(pB0, pB1, (bf16*)((char*)K_lds + SHM_K), qr, r32, hi, j * KVBLK, L);
;       finishSM(pA0, pA1, alA, l_reg, pa0, pa1, pa2, pa3); SBAR(); }
;     SLOAD(SO, (j + 2) * KVBLK); SBAR();
.LBB0_889:
	s_or_b64 exec, exec, s[2:3]
	v_add_co_u32_e32 v2, vcc, 0xffff0000, v170
	v_lshl_add_u64 v[14:15], v[168:169], 0, s[6:7]
	s_nop 0
	v_addc_co_u32_e32 v3, vcc, -1, v171, vcc
	v_add_co_u32_e32 v6, vcc, 0xa160000, v14
	global_load_dwordx4 v[2:5], v[2:3], off
	s_nop 0
	v_addc_co_u32_e32 v7, vcc, 0, v15, vcc
	global_load_dwordx4 v[6:9], v[6:7], off
	s_and_saveexec_b64 s[2:3], s[8:9]
	s_cbranch_execz .LBB0_891
	v_lshl_add_u64 v[140:141], v[166:167], 0, s[6:7]
	v_add_co_u32_e32 v140, vcc, 0xa160000, v140
	s_nop 1
	v_addc_co_u32_e32 v141, vcc, 0, v141, vcc
	global_load_dwordx4 v[140:143], v[140:141], off

; #define SBAR() __builtin_amdgcn_sched_barrier(0)
; #define SLOAD(i, key0) do { sr_[i].v = *reinterpret_cast<const bf16x8*>(&Vh[(long)((key0) + vr) * ldv + vc]); \
;     sr_[i].k0 = *reinterpret_cast<const bf16x8*>(&Kh[(long)((key0) + kr0) * ldk + kc0]); \
;     if (k2) sr_[i].k1 = *reinterpret_cast<const bf16x8*>(&Kh[(long)((key0) + kr1) * ldk + kc1]); } while (0)
; #define SWRITE(b, i) do { *(bf16x8*)((char*)V_lds + (b) * SHM_V + vst) = sr_[i].v; \
;     *(bf16x8*)((char*)K_lds + (b) * SHM_K + ksw0) = sr_[i].k0; \
;     if (k2) *(bf16x8*)((char*)K_lds + (b) * SHM_K + ksw1) = sr_[i].k1; } while (0)
; #define SWAIT() asm volatile("s_waitcnt vmcnt(2)" ::: "memory")
; #define RESC(a) do { if (__any((a) < 1.f)) { if (hi == 0) al_l[r32] = (a); asm volatile("s_waitcnt lgkmcnt(0)" ::: "memory"); \
;     _Pragma("unroll") for (int d = 0; d < 2; ++d) _Pragma("unroll") for (int r = 0; r < 16; ++r) o[d][r] *= al_l[crow(r, hi)]; } } while (0)
; template <int DQK>
; __device__ __forceinline__ void qkt(f32x16& p0, f32x16& p1, const bf16* Ks, const bf16x8* qr, int r32, int hi, int k0, int L) {
;   p0 = f32x16{}; p1 = f32x16{};
; #pragma unroll
;   for (int d0 = 0; d0 < DQK / 16; ++d0) { int cb = (d0 * 16 + hi * 8) * 2;
;     bf16x8 b0 = *reinterpret_cast<const bf16x8*>((const char*)Ks + KSWZ(r32, cb));
;     bf16x8 b1 = *reinterpret_cast<const bf16x8*>((const char*)Ks + KSWZ(32 + r32, cb));
;     p0 = __builtin_amdgcn_mfma_f32_32x32x16_bf16(b0, qr[d0], p0, 0, 0, 0);
;     p1 = __builtin_amdgcn_mfma_f32_32x32x16_bf16(b1, qr[d0], p1, 0, 0, 0); }
; template <int DQK, bool FIX>
; __device__ __forceinline__ void attn_item(const bf16* Qb, const bf16* __restrict__ Kh, const bf16* __restrict__ Vh,
;                                           u16* Ob, int q0, int L, int NT, char* lds, float mC) {
;     ...
;     __syncthreads(); SWAIT(); SWRITE(0, SE);
;     if (act) { RESC(alB); } __syncthreads();
;     if (act) { SBAR(); qkt<DQK>(pA0, pA1, K_lds, qr, r32, hi, (j + 1) * KVBLK, L);
;       finishSM(pB0, pB1, alB, l_reg, pa0, pa1, pa2, pa3); SBAR(); }
;     if (j + 3 < NT) SLOAD(SE, (j + 3) * KVBLK); SBAR();
.LBB0_895:
	s_or_b64 exec, exec, s[2:3]
	s_waitcnt lgkmcnt(0)
	s_barrier
	s_waitcnt vmcnt(2)
	s_waitcnt vmcnt(3)
	ds_write_b128 v193, v[144:147]
	s_waitcnt vmcnt(2)
	ds_write_b128 v194, v[148:151] offset:49152
	s_and_saveexec_b64 s[2:3], s[8:9]
	ds_write_b128 v195, v[136:139] offset:49152
	s_or_b64 exec, exec, s[2:3]
	s_and_saveexec_b64 s[2:3], s[10:11]
	s_cbranch_execz .LBB0_903
	s_add_i32 s14, s4, 0x80
	s_cmp_le_u32 s14, s5
	s_cbranch_scc0 .Lslow96b
	s_and_b64 vcc, exec, s[12:13]
	s_cbranch_vccz .Lslow96b
	ds_read_b128 v[222:225], v200 offset:32768
	ds_read_b128 v[226:229], v200 offset:40960
	ds_read_b128 v[230:233], v201 offset:32768
	ds_read_b128 v[234:237], v201 offset:40960
	ds_read_b128 v[238:241], v202 offset:32768
	ds_read_b128 v[242:245], v202 offset:40960
	ds_read_b128 v[246:249], v203 offset:32768
	ds_read_b128 v[250:253], v203 offset:40960
	v_cvt_pk_bf16_f32 v10, v80, v81
	v_cvt_pk_bf16_f32 v11, v82, v83
	v_cvt_pk_bf16_f32 v12, v84, v85
	v_cvt_pk_bf16_f32 v13, v86, v87
	v_cvt_pk_bf16_f32 v152, v88, v89
	v_cvt_pk_bf16_f32 v153, v90, v91
	v_cvt_pk_bf16_f32 v154, v92, v93
	v_cvt_pk_bf16_f32 v155, v94, v95
	s_waitcnt lgkmcnt(7)
	v_mfma_f32_32x32x16_bf16 v[64:79], v[222:225], v[112:115], 0
	ds_read_b128 v[222:225], v204 offset:32768
	ds_read_b64_tr_b16 v[206:207], v199 offset:0
	ds_read_b64_tr_b16 v[208:209], v199 offset:2048
	ds_read_b64_tr_b16 v[210:211], v199 offset:4096
	ds_read_b64_tr_b16 v[212:213], v199 offset:6144
	v_exp_f32_e32 v96, v96
	v_exp_f32_e32 v97, v97
	v_add_f32_e32 v0, 0, v80
	s_waitcnt lgkmcnt(11)
	v_mfma_f32_32x32x16_bf16 v[48:63], v[226:229], v[112:115], 0
	ds_read_b128 v[226:229], v204 offset:40960
	ds_read_b64_tr_b16 v[214:215], v199 offset:8192
	ds_read_b64_tr_b16 v[216:217], v199 offset:10240
	ds_read_b64_tr_b16 v[218:219], v199 offset:12288
	s_waitcnt lgkmcnt(14)
	ds_read_b64_tr_b16 v[220:221], v199 offset:14336
	v_exp_f32_e32 v98, v98
	v_exp_f32_e32 v99, v99
	v_add_f32_e32 v0, v81, v0
	v_mfma_f32_32x32x16_bf16 v[64:79], v[230:233], v[116:119], v[64:79]
	s_waitcnt lgkmcnt(14)
	ds_read_b128 v[230:233], v205 offset:32768
	v_exp_f32_e32 v100, v100
	v_exp_f32_e32 v101, v101
	v_add_f32_e32 v0, v82, v0
	v_mfma_f32_32x32x16_bf16 v[48:63], v[234:237], v[116:119], v[48:63]
	s_waitcnt lgkmcnt(14)
	ds_read_b128 v[234:237], v205 offset:40960
	v_exp_f32_e32 v102, v102
	v_exp_f32_e32 v103, v103
	v_add_f32_e32 v0, v83, v0
	v_mfma_f32_32x32x16_bf16 v[64:79], v[238:241], v[120:123], v[64:79]
	v_exp_f32_e32 v104, v104
	v_exp_f32_e32 v105, v105
	v_add_f32_e32 v0, v84, v0
	s_waitcnt lgkmcnt(14)
	v_mfma_f32_32x32x16_bf16 v[48:63], v[242:245], v[120:123], v[48:63]
	v_exp_f32_e32 v106, v106
	v_exp_f32_e32 v107, v107
	v_add_f32_e32 v0, v85, v0
	s_waitcnt lgkmcnt(13)
	v_mfma_f32_32x32x16_bf16 v[64:79], v[246:249], v[124:127], v[64:79]
	v_exp_f32_e32 v108, v108
	v_exp_f32_e32 v109, v109
	v_add_f32_e32 v0, v86, v0
	s_waitcnt lgkmcnt(12)
	v_mfma_f32_32x32x16_bf16 v[48:63], v[250:253], v[124:127], v[48:63]
	v_exp_f32_e32 v110, v110
	v_exp_f32_e32 v111, v111
	v_add_f32_e32 v0, v87, v0
	s_waitcnt lgkmcnt(11)
	v_mfma_f32_32x32x16_bf16 v[64:79], v[222:225], v[128:131], v[64:79]
	ds_read_b64_tr_b16 v[238:239], v199 offset:512
	ds_read_b64_tr_b16 v[240:241], v199 offset:2560
	ds_read_b64_tr_b16 v[242:243], v199 offset:4608
	ds_read_b64_tr_b16 v[244:245], v199 offset:6656
	v_cvt_pk_bf16_f32 v156, v96, v97
	v_cvt_pk_bf16_f32 v157, v98, v99
	v_cvt_pk_bf16_f32 v158, v100, v101
	v_cvt_pk_bf16_f32 v159, v102, v103
	v_add_f32_e32 v0, v88, v0
	v_add_f32_e32 v0, v89, v0
	s_waitcnt lgkmcnt(10)
	v_mfma_f32_32x32x16_bf16 v[48:63], v[226:229], v[128:131], v[48:63]
	v_cvt_pk_bf16_f32 v160, v104, v105
	v_cvt_pk_bf16_f32 v161, v106, v107
	v_cvt_pk_bf16_f32 v162, v108, v109
	v_cvt_pk_bf16_f32 v163, v110, v111
	v_add_f32_e32 v0, v90, v0
	v_add_f32_e32 v0, v91, v0
	s_waitcnt lgkmcnt(5)
	v_mfma_f32_32x32x16_bf16 v[64:79], v[230:233], v[132:135], v[64:79]
	ds_read_b64_tr_b16 v[246:247], v199 offset:8704
	ds_read_b64_tr_b16 v[248:249], v199 offset:10752
	ds_read_b64_tr_b16 v[250:251], v199 offset:12800
	ds_read_b64_tr_b16 v[252:253], v199 offset:14848
	v_add_f32_e32 v0, v92, v0
	v_add_f32_e32 v0, v93, v0
	s_waitcnt lgkmcnt(8)
	v_mfma_f32_32x32x16_bf16 v[48:63], v[234:237], v[132:135], v[48:63]
	v_add_f32_e32 v0, v94, v0
	v_add_f32_e32 v0, v95, v0
	s_or_b64 exec, exec, s[2:3]
	s_cmp_ge_u32 s79, s97
	s_cselect_b64 s[2:3], -1, 0
	s_and_b64 vcc, exec, s[2:3]
	s_cbranch_vccnz .Lfast96b_nl
	v_add_co_u32_e32 v14, vcc, 0xa178000, v14
	global_load_dwordx4 v[144:147], v[170:171], off
	s_nop 0
	v_addc_co_u32_e32 v15, vcc, 0, v15, vcc
	global_load_dwordx4 v[148:151], v[14:15], off
	s_and_saveexec_b64 s[14:15], s[8:9]
	s_cbranch_execz .Lfast96b_k2
	v_lshl_add_u64 v[14:15], v[166:167], 0, s[6:7]
	v_add_co_u32_e32 v14, vcc, 0xa178000, v14
	s_nop 1
	v_addc_co_u32_e32 v15, vcc, 0, v15, vcc
	global_load_dwordx4 v[136:139], v[14:15], off

; #define SBAR() __builtin_amdgcn_sched_barrier(0)
; #define SLOAD(i, key0) do { sr_[i].v = *reinterpret_cast<const bf16x8*>(&Vh[(long)((key0) + vr) * ldv + vc]); \
;     sr_[i].k0 = *reinterpret_cast<const bf16x8*>(&Kh[(long)((key0) + kr0) * ldk + kc0]); \
;     if (k2) sr_[i].k1 = *reinterpret_cast<const bf16x8*>(&Kh[(long)((key0) + kr1) * ldk + kc1]); } while (0)
; template <int DQK, bool FIX>
; __device__ __forceinline__ void attn_item(const bf16* Qb, const bf16* __restrict__ Kh, const bf16* __restrict__ Vh,
;                                           u16* Ob, int q0, int L, int NT, char* lds, float mC) {
;     ...
;     if (act) { SBAR(); qkt<DQK>(pA0, pA1, K_lds, qr, r32, hi, (j + 1) * KVBLK, L);
;       finishSM(pB0, pB1, alB, l_reg, pa0, pa1, pa2, pa3); SBAR(); }
;     if (j + 3 < NT) SLOAD(SE, (j + 3) * KVBLK); SBAR();
.LBB0_903:
	s_or_b64 exec, exec, s[2:3]
	s_cmp_ge_u32 s79, s97
	s_cselect_b64 s[2:3], -1, 0
	s_and_b64 vcc, exec, s[2:3]
	s_cbranch_vccnz .LBB0_907
	v_add_co_u32_e32 v14, vcc, 0xa178000, v14
	global_load_dwordx4 v[144:147], v[170:171], off
	s_nop 0
	v_addc_co_u32_e32 v15, vcc, 0, v15, vcc
	global_load_dwordx4 v[148:151], v[14:15], off
	s_and_saveexec_b64 s[14:15], s[8:9]
	s_cbranch_execz .LBB0_906
	v_lshl_add_u64 v[14:15], v[166:167], 0, s[6:7]
	v_add_co_u32_e32 v14, vcc, 0xa178000, v14
	s_nop 1
	v_addc_co_u32_e32 v15, vcc, 0, v15, vcc
	global_load_dwordx4 v[136:139], v[14:15], off

; #define SWRITE(b, i) do { *(bf16x8*)((char*)V_lds + (b) * SHM_V + vst) = sr_[i].v; \
;     *(bf16x8*)((char*)K_lds + (b) * SHM_K + ksw0) = sr_[i].k0; \
;     if (k2) *(bf16x8*)((char*)K_lds + (b) * SHM_K + ksw1) = sr_[i].k1; } while (0)
; #define SWAIT() asm volatile("s_waitcnt vmcnt(2)" ::: "memory")
; #define RESC(a) do { if (__any((a) < 1.f)) { if (hi == 0) al_l[r32] = (a); asm volatile("s_waitcnt lgkmcnt(0)" ::: "memory"); \
;     _Pragma("unroll") for (int d = 0; d < 2; ++d) _Pragma("unroll") for (int r = 0; r < 16; ++r) o[d][r] *= al_l[crow(r, hi)]; } } while (0)
; template <int DQK, bool FIX>
; __device__ __forceinline__ void attn_item(const bf16* Qb, const bf16* __restrict__ Kh, const bf16* __restrict__ Vh,
;                                           u16* Ob, int q0, int L, int NT, char* lds, float mC) {
;     ...
;     if (act) { pv_d0(o, vb0 + (int)SHM_V, pa0, pa1, pa2, pa3); partialSM<DQK, FIX>(pA0, pA1, m_reg, mnA, alA, mC); }
;     __syncthreads(); SWAIT(); SWRITE(1, SO);
;     if (act) { RESC(alA); } __syncthreads();
.LBB0_911:
	s_or_b64 exec, exec, s[14:15]
	s_waitcnt lgkmcnt(0)
	s_barrier
	s_waitcnt vmcnt(2)
	s_and_b64 vcc, exec, s[2:3]
	s_cbranch_vccz .Lt96b_w
	s_waitcnt vmcnt(0)
.Lt96b_w:
	ds_write_b128 v193, v[2:5] offset:16384
	ds_write_b128 v194, v[6:9] offset:32768
	s_and_saveexec_b64 s[14:15], s[8:9]
	s_cbranch_execz .LBB0_882
	ds_write_b128 v195, v[140:143] offset:32768
	s_branch .LBB0_882
